# attention PV: packed v_pk_mul O-rescale beside MFMAs split into scalar v_mul pairs (on top of 288-B stride version)
# baseline (speedup 1.0000x reference)
; __device__ __forceinline__ unsigned cvt_pk_bf16(float lo, float hi) { unsigned r; asm("v_cvt_pk_bf16_f32 %0, %1, %2" : "=v"(r) : "v"(lo), "v"(hi)); return r; }
; #define LAS __attribute__((address_space(3)))
; #define MFMA16(a, b, c) __builtin_amdgcn_mfma_f32_16x16x32_bf16((a), (b), (c), 0, 0, 0)
; #define ATT_STORE(buf_) do { _Pragma("unroll") for (int i = 0; i < 8; ++i) \
;     *(LAS u32x4*)(st0 + (buf_) * ATT_BUF + ((i >> 2) * 2 + ((i >> 1) & 1)) * ATT_TILE + (i & 1) * 32 * 272) = t[i]; } while (0)
; __device__ __forceinline__ void attn_wg_item(const Params& p, int item, LAS unsigned char* lds) {
;     ...
;     tmax = fmaxf(tmax, __shfl_xor(tmax, 16)); tmax = fmaxf(tmax, __shfl_xor(tmax, 32));
;     const float mnew = fmaxf(mrun, tmax), alpha = __builtin_amdgcn_exp2f(mrun - mnew); mrun = mnew;
;     float psum = 0.f;
; #pragma unroll
;     for (int kt = 0; kt < 4; ++kt)
; #pragma unroll
;       for (int i = 0; i < 4; ++i) { const float e = __builtin_amdgcn_exp2f(S[kt][i] - mnew); S[kt][i] = e; psum += e; }
;     lsum = lsum * alpha + psum;
; #pragma unroll
;     for (int dt = 0; dt < 8; ++dt) O[dt] *= alpha;
;     bf16x8 Pf[2];
; #pragma unroll
;     for (int s2 = 0; s2 < 2; ++s2) { u32x4 wv; wv.x = cvt_pk_bf16(S[2 * s2][0], S[2 * s2][1]); wv.y = cvt_pk_bf16(S[2 * s2][2], S[2 * s2][3]);
;       wv.z = cvt_pk_bf16(S[2 * s2 + 1][0], S[2 * s2 + 1][1]); wv.w = cvt_pk_bf16(S[2 * s2 + 1][2], S[2 * s2 + 1][3]); Pf[s2] = __builtin_bit_cast(bf16x8, wv); }
;     { const int qq = l15 >> 2, pp = l15 & 3; LAS unsigned char* vb = Vl + (4 * kq + qq) * 272 + pp * 8;
; #pragma unroll
;       for (int s2 = 0; s2 < 2; ++s2)
; #pragma unroll
;         for (int dt = 0; dt < 8; ++dt) {
;           const s16x4 lo = __builtin_amdgcn_ds_read_tr16_b64_v4i16((LAS s16x4*)(vb + (32 * s2) * 272 + dt * 32));
;           const s16x4 hi = __builtin_amdgcn_ds_read_tr16_b64_v4i16((LAS s16x4*)(vb + (32 * s2 + 16) * 272 + dt * 32));
;           const bf16x8 Vf = __builtin_shufflevector(lo, hi, 0, 1, 2, 3, 4, 5, 6, 7);
;           O[dt] = MFMA16(Vf, Pf[s2], O[dt]); } }
;     if (ps < 8) ATT_STORE((ps + 1) & 1);
.LBB0_822:
	s_or_b64 exec, exec, s[14:15]
	s_waitcnt lgkmcnt(0)
	s_nop 0
	v_add_f32_e32 v136, v83, v136
	v_max_f32_e32 v80, v158, v158
	v_max_f32_e32 v80, v80, v136
	s_andn2_b64 vcc, exec, s[10:11]
	v_mov_b32_e32 v81, v80
	v_mov_b32_e32 v166, v80
	s_nop 1
	v_permlane16_swap_b32_e32 v81, v166
	v_max_f32_e32 v80, v81, v166
	v_mov_b32_e32 v81, v80
	v_mov_b32_e32 v166, v80
	s_nop 1
	v_permlane32_swap_b32_e32 v81, v166
	v_max3_f32 v81, v155, v81, v166
	v_sub_f32_e32 v80, v155, v81
	v_sub_f32_e32 v83, v123, v81
	v_sub_f32_e32 v123, v136, v81
	v_add3_u32 v136, s16, v139, v140
	v_exp_f32_e32 v80, v80
	v_sub_f32_e32 v88, v128, v81
	v_sub_f32_e32 v89, v129, v81
	v_sub_f32_e32 v90, v130, v81
	v_sub_f32_e32 v91, v131, v81
	v_sub_f32_e32 v92, v132, v81
	v_sub_f32_e32 v93, v133, v81
	v_sub_f32_e32 v94, v134, v81
	v_sub_f32_e32 v95, v135, v81
	ds_read_b64_tr_b16 v[184:185], v136 offset:36864
	ds_read_b64_tr_b16 v[186:187], v136 offset:41472
	ds_read_b64_tr_b16 v[188:189], v136 offset:36896
	ds_read_b64_tr_b16 v[190:191], v136 offset:41504
	ds_read_b64_tr_b16 v[192:193], v136 offset:36928
	ds_read_b64_tr_b16 v[194:195], v136 offset:41536
	ds_read_b64_tr_b16 v[196:197], v136 offset:36960
	ds_read_b64_tr_b16 v[198:199], v136 offset:41568
	ds_read_b64_tr_b16 v[200:201], v136 offset:36992
	ds_read_b64_tr_b16 v[202:203], v136 offset:41600
	ds_read_b64_tr_b16 v[204:205], v136 offset:37024
	ds_read_b64_tr_b16 v[206:207], v136 offset:41632
	ds_read_b64_tr_b16 v[208:209], v136 offset:37056
	ds_read_b64_tr_b16 v[210:211], v136 offset:41664
	v_sub_f32_e32 v82, v122, v81
	v_sub_f32_e32 v84, v124, v81
	v_sub_f32_e32 v85, v125, v81
	v_sub_f32_e32 v86, v126, v81
	v_sub_f32_e32 v87, v127, v81
	v_mul_f32_e32 v78, v78, v80
	v_mul_f32_e32 v79, v79, v80
	v_mul_f32_e32 v76, v76, v80
	v_mul_f32_e32 v77, v77, v80
	v_mul_f32_e32 v74, v74, v80
	v_mul_f32_e32 v75, v75, v80
	v_mul_f32_e32 v72, v72, v80
	v_mul_f32_e32 v73, v73, v80
	v_mul_f32_e32 v70, v70, v80
	v_mul_f32_e32 v71, v71, v80
	v_mul_f32_e32 v68, v68, v80
	v_mul_f32_e32 v69, v69, v80
	v_mul_f32_e32 v66, v66, v80
	v_mul_f32_e32 v67, v67, v80
	v_mul_f32_e32 v64, v64, v80
	v_mul_f32_e32 v65, v65, v80
	v_exp_f32_e32 v82, v82
	v_exp_f32_e32 v83, v83
	v_exp_f32_e32 v84, v84
	v_exp_f32_e32 v85, v85
	v_exp_f32_e32 v86, v86
	v_exp_f32_e32 v87, v87
	v_exp_f32_e32 v88, v88
	v_exp_f32_e32 v89, v89
	v_cvt_pk_bf16_f32 v124, v82, v83
	v_cvt_pk_bf16_f32 v125, v84, v85
	v_cvt_pk_bf16_f32 v126, v86, v87
	v_cvt_pk_bf16_f32 v127, v88, v89
	v_mul_f32_e32 v62, v62, v80
	v_mul_f32_e32 v63, v63, v80
	s_waitcnt lgkmcnt(12)
	v_mfma_f32_16x16x32_bf16 v[76:79], v[184:187], v[124:127], v[76:79]
	ds_read_b64_tr_b16 v[212:213], v136 offset:37088
	ds_read_b64_tr_b16 v[214:215], v136 offset:41696
	v_mul_f32_e32 v60, v60, v80
	v_mul_f32_e32 v61, v61, v80
	v_mul_f32_e32 v58, v58, v80
	v_mul_f32_e32 v59, v59, v80
	s_waitcnt lgkmcnt(12)
	v_mfma_f32_16x16x32_bf16 v[72:75], v[188:191], v[124:127], v[72:75]
	ds_read_b64_tr_b16 v[216:217], v136 offset:46080
	ds_read_b64_tr_b16 v[218:219], v136 offset:50688
	v_mul_f32_e64 v56, v56, v80
	v_mul_f32_e64 v57, v57, v80
	v_mul_f32_e32 v38, v38, v80
	v_mul_f32_e32 v39, v39, v80
	v_mul_f32_e32 v36, v36, v80
	v_mul_f32_e32 v37, v37, v80
	s_waitcnt lgkmcnt(12)
	v_mfma_f32_16x16x32_bf16 v[68:71], v[192:195], v[124:127], v[68:71]
	ds_read_b64_tr_b16 v[220:221], v136 offset:46112
	ds_read_b64_tr_b16 v[222:223], v136 offset:50720
	v_mul_f32_e64 v30, v30, v80
	v_mul_f32_e64 v31, v31, v80
	v_mul_f32_e32 v28, v28, v80
	v_mul_f32_e32 v29, v29, v80
	v_sub_f32_e32 v122, v157, v81
	s_waitcnt lgkmcnt(12)
	v_mfma_f32_16x16x32_bf16 v[64:67], v[196:199], v[124:127], v[64:67]
	ds_read_b64_tr_b16 v[224:225], v136 offset:46144
	ds_read_b64_tr_b16 v[226:227], v136 offset:50752
	v_exp_f32_e32 v90, v90
	v_exp_f32_e32 v91, v91
	s_waitcnt lgkmcnt(12)
	v_mfma_f32_16x16x32_bf16 v[60:63], v[200:203], v[124:127], v[60:63]
	ds_read_b64_tr_b16 v[228:229], v136 offset:46176
	ds_read_b64_tr_b16 v[230:231], v136 offset:50784
	v_exp_f32_e32 v92, v92
	v_exp_f32_e32 v93, v93
	v_exp_f32_e32 v94, v94
	s_waitcnt lgkmcnt(12)
	v_mfma_f32_16x16x32_bf16 v[56:59], v[204:207], v[124:127], v[56:59]
	ds_read_b64_tr_b16 v[232:233], v136 offset:46208
	ds_read_b64_tr_b16 v[234:235], v136 offset:50816
	v_exp_f32_e32 v95, v95
	v_exp_f32_e32 v122, v122
	s_waitcnt lgkmcnt(12)
	v_mfma_f32_16x16x32_bf16 v[36:39], v[208:211], v[124:127], v[36:39]
	ds_read_b64_tr_b16 v[236:237], v136 offset:46240
	ds_read_b64_tr_b16 v[238:239], v136 offset:50848
	v_exp_f32_e32 v123, v123
	v_cvt_pk_bf16_f32 v128, v90, v91
	v_cvt_pk_bf16_f32 v129, v92, v93
	s_waitcnt lgkmcnt(12)
	v_mfma_f32_16x16x32_bf16 v[28:31], v[212:215], v[124:127], v[28:31]
	ds_read_b64_tr_b16 v[240:241], v136 offset:46272
	ds_read_b64_tr_b16 v[242:243], v136 offset:50880
	v_cvt_pk_bf16_f32 v130, v94, v95
	v_cvt_pk_bf16_f32 v131, v122, v123
	s_nop 1
	s_waitcnt lgkmcnt(12)
	v_mfma_f32_16x16x32_bf16 v[76:79], v[216:219], v[128:131], v[76:79]
	ds_read_b64_tr_b16 v[172:173], v136 offset:46304
	ds_read_b64_tr_b16 v[174:175], v136 offset:50912
	s_waitcnt lgkmcnt(12)
	v_mfma_f32_16x16x32_bf16 v[72:75], v[220:223], v[128:131], v[72:75]
	s_waitcnt lgkmcnt(10)
	v_mfma_f32_16x16x32_bf16 v[68:71], v[224:227], v[128:131], v[68:71]
	s_waitcnt lgkmcnt(8)
	v_mfma_f32_16x16x32_bf16 v[64:67], v[228:231], v[128:131], v[64:67]
	s_waitcnt lgkmcnt(6)
	v_mfma_f32_16x16x32_bf16 v[60:63], v[232:235], v[128:131], v[60:63]
	s_waitcnt lgkmcnt(4)
	v_mfma_f32_16x16x32_bf16 v[56:59], v[236:239], v[128:131], v[56:59]
	s_waitcnt lgkmcnt(2)
	v_mfma_f32_16x16x32_bf16 v[36:39], v[240:243], v[128:131], v[36:39]
	s_waitcnt lgkmcnt(0)
	v_mfma_f32_16x16x32_bf16 v[28:31], v[172:175], v[128:131], v[28:31]
	s_cbranch_vccnz .LBB0_824
	s_andn2_b32 s10, 1, s8
	s_mul_i32 s10, s10, 0x12000
	v_add_u32_e32 v124, s10, v137
	s_waitcnt vmcnt(0)
	ds_write_b128 v124, v[0:3]
	ds_write_b128 v124, v[8:11] offset:9216
	ds_write_b128 v124, v[4:7] offset:18432
	ds_write_b128 v124, v[16:19] offset:27648
	ds_write_b128 v124, v[12:15] offset:36864
	ds_write_b128 v124, v[24:27] offset:46080
	ds_write_b128 v124, v[20:23] offset:55296
	ds_write_b128 v124, v[32:35] offset:64512
